# early acquire: buffer_inv issued at barrier arrival (members before polling, leader with wbl2) instead of after release
# speedup vs baseline: 1.0375x; 1.0160x over previous
.LBB0_129:
	s_or_b64 exec, exec, s[10:11]
	v_cvt_f32_u32_e32 v4, v2
	s_waitcnt vmcnt(0)
	v_readfirstlane_b32 s0, v3
	v_sub_u32_e32 v3, 0, v2
	v_rcp_iflag_f32_e32 v4, v4
	v_add_u32_e32 v5, s0, v1
	v_mul_f32_e32 v4, 0x4f7ffffe, v4
	v_cvt_u32_f32_e32 v4, v4
	v_mul_lo_u32 v1, v3, v4
	v_mul_hi_u32 v1, v4, v1
	v_add_u32_e32 v1, v4, v1
	v_mul_hi_u32 v1, v5, v1
	v_mul_lo_u32 v3, v1, v2
	v_sub_u32_e32 v3, v5, v3
	v_add_u32_e32 v4, 1, v1
	v_cmp_ge_u32_e32 vcc, v3, v2
	s_nop 1
	v_cndmask_b32_e32 v1, v1, v4, vcc
	v_sub_u32_e32 v4, v3, v2
	v_cndmask_b32_e32 v3, v3, v4, vcc
	v_add_u32_e32 v4, 1, v1
	v_cmp_ge_u32_e32 vcc, v3, v2
	v_add_u32_e32 v3, 1, v5
	s_nop 0
	v_cndmask_b32_e32 v1, v1, v4, vcc
	v_mul_lo_u32 v4, v2, v1
	v_add_u32_e32 v2, v4, v2
	v_cmp_ne_u32_e32 vcc, v3, v2
	s_and_saveexec_b64 s[0:1], vcc
	s_xor_b64 s[8:9], exec, s[0:1]
	s_cbranch_execz .LBB0_143
	s_waitcnt lgkmcnt(0)
	buffer_inv sc1
	v_mov_b32_e32 v0, 0x2000
	global_load_dword v0, v0, s[6:7] offset:1024 sc1
	s_add_u32 s14, s6, 0x2400
	s_addc_u32 s15, s7, 0
	s_waitcnt vmcnt(0)
	v_cmp_eq_u32_e32 vcc, v0, v1
	s_and_saveexec_b64 s[10:11], vcc
	s_cbranch_execz .LBB0_142
	s_add_u32 s12, s30, 0xda68a00
	s_addc_u32 s13, s31, 0
	s_mov_b32 s0, 1
	s_mov_b64 s[16:17], 0
	v_mov_b32_e32 v0, 0
	s_branch .LBB0_133

.LBB0_142:
	s_or_b64 exec, exec, s[10:11]
	s_waitcnt vmcnt(0)
	s_waitcnt vmcnt(0)
.LBB0_143:
	s_andn2_saveexec_b64 s[0:1], s[8:9]
	s_cbranch_execz .LBB0_163
	s_mov_b64 s[8:9], exec
	buffer_wbl2 sc1
	buffer_inv sc1
	s_waitcnt lgkmcnt(0)
	s_waitcnt vmcnt(0)
	v_mbcnt_lo_u32_b32 v1, s8, 0
	v_mbcnt_hi_u32_b32 v1, s9, v1
	v_cmp_eq_u32_e32 vcc, 0, v1
	s_and_saveexec_b64 s[10:11], vcc
	s_cbranch_execz .LBB0_146
	s_bcnt1_i32_b64 s0, s[8:9]
	v_mov_b32_e32 v2, 0xda6b000
	v_mov_b32_e32 v3, s0
	global_atomic_add v2, v2, v3, s[30:31] offset:3072 sc0

.LBB0_160:
	s_or_b64 exec, exec, s[8:9]
	s_mov_b64 s[8:9], exec
	v_mbcnt_lo_u32_b32 v0, s8, 0
	v_mbcnt_hi_u32_b32 v0, s9, v0
	v_cmp_eq_u32_e32 vcc, 0, v0
	s_waitcnt vmcnt(0)
	s_and_saveexec_b64 s[10:11], vcc
	s_cbranch_execz .LBB0_162
	s_bcnt1_i32_b64 s0, s[8:9]
	v_mov_b32_e32 v0, 0x2000
	v_mov_b32_e32 v1, s0

.LBB0_250:
	s_or_b64 exec, exec, s[14:15]
	v_cvt_f32_u32_e32 v4, v2
	s_waitcnt vmcnt(0)
	v_readfirstlane_b32 s0, v3
	v_sub_u32_e32 v3, 0, v2
	v_rcp_iflag_f32_e32 v4, v4
	v_add_u32_e32 v5, s0, v1
	v_mul_f32_e32 v4, 0x4f7ffffe, v4
	v_cvt_u32_f32_e32 v4, v4
	v_mul_lo_u32 v1, v3, v4
	v_mul_hi_u32 v1, v4, v1
	v_add_u32_e32 v1, v4, v1
	v_mul_hi_u32 v1, v5, v1
	v_mul_lo_u32 v3, v1, v2
	v_sub_u32_e32 v3, v5, v3
	v_add_u32_e32 v4, 1, v1
	v_cmp_ge_u32_e32 vcc, v3, v2
	s_nop 1
	v_cndmask_b32_e32 v1, v1, v4, vcc
	v_sub_u32_e32 v4, v3, v2
	v_cndmask_b32_e32 v3, v3, v4, vcc
	v_add_u32_e32 v4, 1, v1
	v_cmp_ge_u32_e32 vcc, v3, v2
	v_add_u32_e32 v3, 1, v5
	s_nop 0
	v_cndmask_b32_e32 v1, v1, v4, vcc
	v_mul_lo_u32 v4, v2, v1
	v_add_u32_e32 v2, v4, v2
	v_cmp_ne_u32_e32 vcc, v3, v2
	s_and_saveexec_b64 s[0:1], vcc
	s_xor_b64 s[8:9], exec, s[0:1]
	s_cbranch_execz .LBB0_264
	s_waitcnt lgkmcnt(0)
	buffer_inv sc1
	v_mov_b32_e32 v0, 0x2000
	global_load_dword v0, v0, s[6:7] offset:1024 sc1
	s_add_u32 s18, s6, 0x2400
	s_addc_u32 s19, s7, 0
	s_waitcnt vmcnt(0)
	v_cmp_eq_u32_e32 vcc, v0, v1
	s_and_saveexec_b64 s[14:15], vcc
	s_cbranch_execz .LBB0_263
	s_add_u32 s16, s30, 0xda68a00
	s_addc_u32 s17, s31, 0
	s_mov_b32 s0, 1
	s_mov_b64 s[20:21], 0
	v_mov_b32_e32 v0, 0
	s_branch .LBB0_254

.LBB0_263:
	s_or_b64 exec, exec, s[14:15]
	s_waitcnt vmcnt(0)
	s_waitcnt vmcnt(0)
.LBB0_264:
	s_andn2_saveexec_b64 s[0:1], s[8:9]
	s_cbranch_execz .LBB0_284
	s_mov_b64 s[8:9], exec
	buffer_wbl2 sc1
	buffer_inv sc1
	s_waitcnt lgkmcnt(0)
	s_waitcnt vmcnt(0)
	v_mbcnt_lo_u32_b32 v1, s8, 0
	v_mbcnt_hi_u32_b32 v1, s9, v1
	v_cmp_eq_u32_e32 vcc, 0, v1
	s_and_saveexec_b64 s[14:15], vcc
	s_cbranch_execz .LBB0_267
	s_bcnt1_i32_b64 s0, s[8:9]
	v_mov_b32_e32 v2, 0xda6b000
	v_mov_b32_e32 v3, s0
	global_atomic_add v2, v2, v3, s[30:31] offset:3072 sc0

.LBB0_281:
	s_or_b64 exec, exec, s[8:9]
	s_mov_b64 s[8:9], exec
	v_mbcnt_lo_u32_b32 v0, s8, 0
	v_mbcnt_hi_u32_b32 v0, s9, v0
	v_cmp_eq_u32_e32 vcc, 0, v0
	s_waitcnt vmcnt(0)
	s_and_saveexec_b64 s[14:15], vcc
	s_cbranch_execz .LBB0_283
	s_bcnt1_i32_b64 s0, s[8:9]
	v_mov_b32_e32 v0, 0x2000
	v_mov_b32_e32 v1, s0

.LBB0_568:
	s_or_b64 exec, exec, s[6:7]
	v_cvt_f32_u32_e32 v4, v2
	s_waitcnt vmcnt(0)
	v_readfirstlane_b32 s4, v3
	v_sub_u32_e32 v3, 0, v2
	v_rcp_iflag_f32_e32 v4, v4
	v_add_u32_e32 v5, s4, v1
	v_mul_f32_e32 v4, 0x4f7ffffe, v4
	v_cvt_u32_f32_e32 v4, v4
	v_mul_lo_u32 v1, v3, v4
	v_mul_hi_u32 v1, v4, v1
	v_add_u32_e32 v1, v4, v1
	v_mul_hi_u32 v1, v5, v1
	v_mul_lo_u32 v3, v1, v2
	v_sub_u32_e32 v3, v5, v3
	v_add_u32_e32 v4, 1, v1
	v_cmp_ge_u32_e32 vcc, v3, v2
	s_nop 1
	v_cndmask_b32_e32 v1, v1, v4, vcc
	v_sub_u32_e32 v4, v3, v2
	v_cndmask_b32_e32 v3, v3, v4, vcc
	v_add_u32_e32 v4, 1, v1
	v_cmp_ge_u32_e32 vcc, v3, v2
	v_add_u32_e32 v3, 1, v5
	s_nop 0
	v_cndmask_b32_e32 v1, v1, v4, vcc
	v_mul_lo_u32 v4, v2, v1
	v_add_u32_e32 v2, v4, v2
	v_cmp_ne_u32_e32 vcc, v3, v2
	s_and_saveexec_b64 s[4:5], vcc
	s_xor_b64 s[4:5], exec, s[4:5]
	s_cbranch_execz .LBB0_582
	s_waitcnt lgkmcnt(0)
	buffer_inv sc1
	v_mov_b32_e32 v0, 0x2000
	global_load_dword v0, v0, s[0:1] offset:1024 sc1
	s_add_u32 s10, s0, 0x2400
	s_addc_u32 s11, s1, 0
	s_waitcnt vmcnt(0)
	v_cmp_eq_u32_e32 vcc, v0, v1
	s_and_saveexec_b64 s[6:7], vcc
	s_cbranch_execz .LBB0_581
	s_add_u32 s8, s30, 0xda68a00
	s_addc_u32 s9, s31, 0
	s_mov_b32 s22, 1
	s_mov_b64 s[12:13], 0
	v_mov_b32_e32 v0, 0
	s_branch .LBB0_572

.LBB0_581:
	s_or_b64 exec, exec, s[6:7]
	s_waitcnt vmcnt(0)
	s_waitcnt vmcnt(0)
.LBB0_582:
	s_andn2_saveexec_b64 s[4:5], s[4:5]
	s_cbranch_execz .LBB0_602
	s_mov_b64 s[4:5], exec
	buffer_wbl2 sc1
	buffer_inv sc1
	s_waitcnt lgkmcnt(0)
	s_waitcnt vmcnt(0)
	v_mbcnt_lo_u32_b32 v1, s4, 0
	v_mbcnt_hi_u32_b32 v1, s5, v1
	v_cmp_eq_u32_e32 vcc, 0, v1
	s_and_saveexec_b64 s[6:7], vcc
	s_cbranch_execz .LBB0_585
	s_bcnt1_i32_b64 s4, s[4:5]
	v_mov_b32_e32 v2, 0xda6b000
	v_mov_b32_e32 v3, s4
	global_atomic_add v2, v2, v3, s[30:31] offset:3072 sc0

.LBB0_599:
	s_or_b64 exec, exec, s[4:5]
	s_mov_b64 s[4:5], exec
	v_mbcnt_lo_u32_b32 v0, s4, 0
	v_mbcnt_hi_u32_b32 v0, s5, v0
	v_cmp_eq_u32_e32 vcc, 0, v0
	s_waitcnt vmcnt(0)
	s_and_saveexec_b64 s[6:7], vcc
	s_cbranch_execz .LBB0_601
	s_bcnt1_i32_b64 s4, s[4:5]
	v_mov_b32_e32 v0, 0x2000
	v_mov_b32_e32 v1, s4
